# P9 EpiZg main epilogue: dummy dword loads touch the cache lines of row groups 1..7 up front (serial in-place chain then hits cache)
# speedup vs baseline: 1.0040x; 1.0029x over previous
.LBB0_2919:
	v_lshl_add_u32 v154, s4, 8, v163
	v_ashrrev_i32_e32 v155, 31, v154
	v_lshlrev_b64 v[156:157], 6, v[154:155]
	v_lshl_add_u64 v[156:157], v[138:139], 0, v[156:157]
	global_load_dwordx4 v[172:175], v[156:157], off
	v_lshl_or_b32 v150, s5, 7, v165
	v_ashrrev_i32_e32 v151, 31, v150
	s_lshl_b32 s4, s5, 3
	v_lshlrev_b64 v[150:151], 1, v[150:151]
	s_ashr_i32 s5, s4, 31
	v_lshl_add_u64 v[152:153], s[14:15], 0, v[150:151]
	s_lshl_b64 s[4:5], s[4:5], 2
	v_lshlrev_b64 v[158:159], 11, v[154:155]
	v_lshl_add_u64 v[196:197], v[152:153], 0, v[158:159]
	s_add_u32 s44, s56, s4
	global_load_dwordx4 v[176:179], v[196:197], off
	s_addc_u32 s45, s57, s5
	v_lshlrev_b64 v[156:157], 8, v[154:155]
	v_lshl_add_u64 v[156:157], s[44:45], 0, v[156:157]
	global_load_dwordx4 v[180:183], v[156:157], off
	global_load_dwordx4 v[184:187], v[156:157], off offset:16
	global_load_dwordx4 v[188:191], v[140:141], off
	global_load_dwordx4 v[192:195], v[140:141], off offset:16
	v_lshlrev_b64 v[202:203], 6, v[154:155]
	v_lshl_add_u64 v[202:203], v[138:139], 0, v[202:203]
	s_mov_b32 s47, 0
	s_mov_b32 s46, 0x2000
	v_lshl_add_u64 v[236:237], v[202:203], 0, s[46:47]
	global_load_dword v200, v[202:203], off offset:1024
	s_mov_b32 s46, 0x1000
	v_lshl_add_u64 v[204:205], v[156:157], 0, s[46:47]
	global_load_dword v200, v[204:205], off
	s_mov_b32 s46, 0x8000
	v_lshl_add_u64 v[206:207], v[196:197], 0, s[46:47]
	global_load_dword v200, v[206:207], off
	global_load_dword v200, v[202:203], off offset:2048
	s_mov_b32 s46, 0x2000
	v_lshl_add_u64 v[208:209], v[156:157], 0, s[46:47]
	global_load_dword v200, v[208:209], off
	s_mov_b32 s46, 0x10000
	v_lshl_add_u64 v[210:211], v[196:197], 0, s[46:47]
	global_load_dword v200, v[210:211], off
	global_load_dword v200, v[202:203], off offset:3072
	s_mov_b32 s46, 0x3000
	v_lshl_add_u64 v[212:213], v[156:157], 0, s[46:47]
	global_load_dword v200, v[212:213], off
	s_mov_b32 s46, 0x18000
	v_lshl_add_u64 v[214:215], v[196:197], 0, s[46:47]
	global_load_dword v200, v[214:215], off
	global_load_dword v200, v[236:237], off offset:0
	s_mov_b32 s46, 0x8000
	v_lshl_add_u64 v[216:217], v[156:157], 0, s[46:47]
	global_load_dword v200, v[216:217], off
	s_mov_b32 s46, 0x40000
	v_lshl_add_u64 v[218:219], v[196:197], 0, s[46:47]
	global_load_dword v200, v[218:219], off
	global_load_dword v200, v[236:237], off offset:1024
	s_mov_b32 s46, 0x9000
	v_lshl_add_u64 v[220:221], v[156:157], 0, s[46:47]
	global_load_dword v200, v[220:221], off
	s_mov_b32 s46, 0x48000
	v_lshl_add_u64 v[222:223], v[196:197], 0, s[46:47]
	global_load_dword v200, v[222:223], off
	global_load_dword v200, v[236:237], off offset:2048
	s_mov_b32 s46, 0xa000
	v_lshl_add_u64 v[224:225], v[156:157], 0, s[46:47]
	global_load_dword v200, v[224:225], off
	s_mov_b32 s46, 0x50000
	v_lshl_add_u64 v[226:227], v[196:197], 0, s[46:47]
	global_load_dword v200, v[226:227], off
	global_load_dword v200, v[236:237], off offset:3072
	s_mov_b32 s46, 0xb000
	v_lshl_add_u64 v[228:229], v[156:157], 0, s[46:47]
	global_load_dword v200, v[228:229], off
	s_mov_b32 s46, 0x58000
	v_lshl_add_u64 v[230:231], v[196:197], 0, s[46:47]
	global_load_dword v200, v[230:231], off
	v_and_b32_e32 v170, 64, v169
	v_xor_b32_e32 v155, 16, v169
	v_add_u32_e32 v170, 64, v170
	v_xor_b32_e32 v171, 32, v169
	v_cmp_lt_i32_e32 vcc, v155, v170
	v_mov_b64_e32 v[156:157], s[20:21]
	v_lshl_add_u64 v[150:151], s[64:65], 0, v[150:151]
	v_cndmask_b32_e32 v155, v169, v155, vcc
	v_cmp_lt_i32_e32 vcc, v171, v170
	v_lshlrev_b32_e32 v170, 2, v155
	s_waitcnt vmcnt(21)
	v_mov_b32_e32 v198, v173
	v_mov_b32_e32 v199, v174
	v_mov_b32_e32 v173, v175
	v_cndmask_b32_e32 v171, v169, v171, vcc
	v_pk_add_f32 v[172:173], v[198:199], v[172:173]
	v_lshlrev_b32_e32 v155, 2, v171
	v_add_f32_e32 v171, v172, v173
	ds_bpermute_b32 v198, v170, v171
	v_lshlrev_b32_e32 v174, 16, v176
	v_mov_b32_e32 v172, v180
	v_mov_b32_e32 v173, v184
	v_mov_b32_e32 v184, v181
	v_mov_b32_e32 v181, v186
	v_mov_b32_e32 v186, v183
	s_waitcnt lgkmcnt(0)
	v_add_f32_e32 v183, v171, v198
	v_pk_add_f32 v[172:173], v[172:173], v[184:185]
	ds_bpermute_b32 v185, v155, v183
	v_mov_b32_e32 v180, v182
	v_pk_add_f32 v[180:181], v[180:181], v[186:187]
	v_and_b32_e32 v175, 0xffff0000, v176
	v_pk_add_f32 v[172:173], v[172:173], v[180:181]
	v_lshlrev_b32_e32 v176, 16, v177
	v_mov_b32_e32 v182, v172
	v_mov_b32_e32 v184, v173
	s_waitcnt lgkmcnt(0)
	v_pk_add_f32 v[172:173], v[182:183], v[184:185]
	v_and_b32_e32 v177, 0xffff0000, v177
	v_pk_fma_f32 v[172:173], v[172:173], s[18:19], v[156:157] op_sel_hi:[1,1,0]
	s_nop 0
	v_mul_f32_e32 v171, 0x4b800000, v173
	v_cmp_gt_f32_e32 vcc, s60, v173
	v_mul_f32_e32 v180, 0x4b800000, v172
	v_cmp_gt_f32_e64 s[4:5], s60, v172
	v_cndmask_b32_e32 v171, v173, v171, vcc
	v_rsq_f32_e32 v171, v171
	v_cndmask_b32_e64 v172, v172, v180, s[4:5]
	v_rsq_f32_e32 v180, v172
	v_lshlrev_b32_e32 v172, 16, v178
	v_and_b32_e32 v173, 0xffff0000, v178
	v_mul_f32_e32 v178, 0x45800000, v171
	v_mul_f32_e32 v181, 0x45800000, v180
	v_cndmask_b32_e32 v178, v171, v178, vcc
	v_cndmask_b32_e64 v180, v180, v181, s[4:5]
	v_pk_mul_f32 v[126:127], v[126:127], v[178:179] op_sel_hi:[1,0]
	v_pk_mul_f32 v[128:129], v[128:129], v[178:179] op_sel_hi:[1,0]
	v_pk_mul_f32 v[124:125], v[124:125], v[178:179] op_sel_hi:[1,0]
	v_pk_mul_f32 v[122:123], v[122:123], v[178:179] op_sel_hi:[1,0]
	v_pk_mul_f32 v[120:121], v[120:121], v[178:179] op_sel_hi:[1,0]
	v_pk_mul_f32 v[118:119], v[118:119], v[178:179] op_sel_hi:[1,0]
	v_pk_mul_f32 v[182:183], v[116:117], v[178:179] op_sel_hi:[1,0]
	v_pk_mul_f32 v[184:185], v[114:115], v[178:179] op_sel_hi:[1,0]
	v_pk_mul_f32 v[116:117], v[188:189], v[180:181] op_sel_hi:[1,0]
	v_mul_f32_e32 v171, 0xbfb8aa3b, v126
	v_mul_f32_e32 v178, 0xbfb8aa3b, v127
	v_pk_mul_f32 v[114:115], v[190:191], v[180:181] op_sel_hi:[1,0]
	v_pk_mul_f32 v[116:117], v[116:117], v[174:175]
	v_mul_f32_e32 v174, 0xbfb8aa3b, v128
	v_mul_f32_e32 v175, 0xbfb8aa3b, v129
	v_exp_f32_e32 v171, v171
	v_exp_f32_e32 v178, v178
	v_pk_mul_f32 v[114:115], v[114:115], v[176:177]
	v_mul_f32_e32 v176, 0xbfb8aa3b, v122
	v_mul_f32_e32 v177, 0xbfb8aa3b, v123
	v_exp_f32_e32 v174, v174
	v_exp_f32_e32 v175, v175
	v_exp_f32_e32 v176, v176
	v_exp_f32_e32 v177, v177
	v_pk_mul_f32 v[186:187], v[194:195], v[180:181] op_sel_hi:[1,0]
	v_pk_mul_f32 v[180:181], v[192:193], v[180:181] op_sel_hi:[1,0]
	v_add_f32_e32 v171, 1.0, v171
	v_add_f32_e32 v178, 1.0, v178
	v_pk_mul_f32 v[172:173], v[180:181], v[172:173]
	v_add_f32_e32 v180, 1.0, v174
	v_add_f32_e32 v181, 1.0, v175
	v_rcp_f32_e32 v174, v171
	v_rcp_f32_e32 v175, v178
	v_add_f32_e32 v188, 1.0, v176
	v_add_f32_e32 v189, 1.0, v177
	v_rcp_f32_e32 v176, v180
	v_rcp_f32_e32 v177, v181
	v_pk_mul_f32 v[126:127], v[126:127], v[174:175]
	v_rcp_f32_e32 v180, v188
	v_rcp_f32_e32 v181, v189
	v_mul_f32_e32 v171, 0xbfb8aa3b, v124
	v_pk_mul_f32 v[128:129], v[128:129], v[176:177]
	v_pk_mul_f32 v[116:117], v[116:117], v[126:127]
	v_pk_mul_f32 v[126:127], v[114:115], v[128:129]
	v_cvt_pk_bf16_f32 v114, v116, v117
	v_exp_f32_e32 v117, v171
	v_mul_f32_e32 v116, 0xbfb8aa3b, v125
	v_cvt_pk_bf16_f32 v115, v126, v127
	v_exp_f32_e32 v126, v116
	v_pk_mul_f32 v[122:123], v[122:123], v[180:181]
	v_add_f32_e32 v117, 1.0, v117
	v_pk_mul_f32 v[122:123], v[172:173], v[122:123]
	v_mul_f32_e32 v118, 0xbfb8aa3b, v118
	v_cvt_pk_bf16_f32 v116, v122, v123
	v_rcp_f32_e32 v122, v117
	v_add_f32_e32 v117, 1.0, v126
	v_rcp_f32_e32 v123, v117
	v_mul_f32_e32 v119, 0xbfb8aa3b, v119
	v_lshlrev_b32_e32 v126, 16, v179
	v_and_b32_e32 v127, 0xffff0000, v179
	v_exp_f32_e32 v118, v118
	v_exp_f32_e32 v119, v119
	v_pk_mul_f32 v[126:127], v[186:187], v[126:127]
	v_pk_mul_f32 v[122:123], v[124:125], v[122:123]
	s_nop 0
	v_pk_mul_f32 v[122:123], v[126:127], v[122:123]
	s_nop 0
	v_cvt_pk_bf16_f32 v117, v122, v123
	global_store_dwordx4 v[196:197], v[114:117], off
	s_nop 1
	v_add_f32_e32 v114, 1.0, v118
	v_add_f32_e32 v115, 1.0, v119
	v_mul_f32_e32 v116, 0xbfb8aa3b, v120
	v_mul_f32_e32 v117, 0xbfb8aa3b, v121
	v_mul_f32_e32 v118, 0xbfb8aa3b, v184
	v_mul_f32_e32 v119, 0xbfb8aa3b, v185
	v_exp_f32_e32 v116, v116
	v_exp_f32_e32 v117, v117
	v_exp_f32_e32 v118, v118
	v_exp_f32_e32 v119, v119
	v_mul_f32_e32 v120, 0xbfb8aa3b, v182
	v_mul_f32_e32 v121, 0xbfb8aa3b, v183
	v_exp_f32_e32 v120, v120
	v_exp_f32_e32 v121, v121
	v_add_f32_e32 v116, 1.0, v116
	v_add_f32_e32 v117, 1.0, v117
	v_add_f32_e32 v118, 1.0, v118
	v_add_f32_e32 v119, 1.0, v119
	v_rcp_f32_e32 v114, v114
	v_rcp_f32_e32 v115, v115
	v_rcp_f32_e32 v116, v116
	v_rcp_f32_e32 v117, v117
	v_rcp_f32_e32 v118, v118
	v_rcp_f32_e32 v119, v119
	v_add_f32_e32 v120, 1.0, v120
	v_add_f32_e32 v121, 1.0, v121
	v_rcp_f32_e32 v120, v120
	v_rcp_f32_e32 v121, v121
	v_cvt_pk_bf16_f32 v114, v114, v115
	v_cvt_pk_bf16_f32 v115, v116, v117
	v_cvt_pk_bf16_f32 v116, v118, v119
	v_lshl_add_u64 v[118:119], v[150:151], 0, v[158:159]
	v_or_b32_e32 v158, 16, v154
	v_cvt_pk_bf16_f32 v117, v120, v121
	v_ashrrev_i32_e32 v159, 31, v158
	global_store_dwordx4 v[118:119], v[114:117], off
	v_lshlrev_b64 v[118:119], 8, v[158:159]
	v_lshl_add_u64 v[122:123], s[44:45], 0, v[118:119]
	v_lshlrev_b64 v[114:115], 6, v[158:159]
	v_lshl_add_u64 v[114:115], v[138:139], 0, v[114:115]
	global_load_dwordx4 v[114:117], v[114:115], off
	s_nop 0
	global_load_dwordx4 v[118:121], v[122:123], off
	s_nop 0
	global_load_dwordx4 v[122:125], v[122:123], off offset:16
	s_nop 0
	global_load_dwordx4 v[126:129], v[140:141], off
	global_load_dwordx4 v[172:175], v[140:141], off offset:16
	v_lshlrev_b64 v[158:159], 11, v[158:159]
	v_lshl_add_u64 v[180:181], v[152:153], 0, v[158:159]
	global_load_dwordx4 v[176:179], v[180:181], off
	s_waitcnt vmcnt(5)
	v_mov_b32_e32 v182, v115
	v_mov_b32_e32 v183, v116
	v_mov_b32_e32 v115, v117
	v_pk_add_f32 v[114:115], v[182:183], v[114:115]
	s_waitcnt vmcnt(4)
	v_mov_b32_e32 v116, v118
	v_add_f32_e32 v118, v114, v115
	s_waitcnt vmcnt(3)
	v_mov_b32_e32 v117, v122
	v_mov_b32_e32 v122, v119
	ds_bpermute_b32 v119, v170, v118
	v_mov_b32_e32 v115, v124
	v_mov_b32_e32 v124, v121
	v_mov_b32_e32 v114, v120
	v_pk_add_f32 v[116:117], v[116:117], v[122:123]
	s_waitcnt lgkmcnt(0)
	v_add_f32_e32 v119, v118, v119
	ds_bpermute_b32 v121, v155, v119
	v_pk_add_f32 v[114:115], v[114:115], v[124:125]
	s_waitcnt vmcnt(0)
	v_and_b32_e32 v125, 0xffff0000, v176
	v_pk_add_f32 v[114:115], v[116:117], v[114:115]
	s_nop 0
	v_mov_b32_e32 v118, v114
	v_mov_b32_e32 v120, v115
	s_waitcnt lgkmcnt(0)
	v_pk_add_f32 v[114:115], v[118:119], v[120:121]
	s_nop 0
	v_pk_fma_f32 v[114:115], v[114:115], s[18:19], v[156:157] op_sel_hi:[1,1,0]
	s_nop 0
	v_mul_f32_e32 v116, 0x4b800000, v115
	v_cmp_gt_f32_e32 vcc, s60, v115
	v_mul_f32_e32 v117, 0x4b800000, v114
	v_cmp_gt_f32_e64 s[4:5], s60, v114
	v_cndmask_b32_e32 v115, v115, v116, vcc
	v_rsq_f32_e32 v115, v115
	v_cndmask_b32_e64 v114, v114, v117, s[4:5]
	v_rsq_f32_e32 v118, v114
	v_mul_f32_e32 v114, 0x45800000, v115
	v_cndmask_b32_e32 v114, v115, v114, vcc
	v_pk_mul_f32 v[112:113], v[112:113], v[114:115] op_sel_hi:[1,0]
	v_pk_mul_f32 v[110:111], v[110:111], v[114:115] op_sel_hi:[1,0]
	v_pk_mul_f32 v[108:109], v[108:109], v[114:115] op_sel_hi:[1,0]
	v_pk_mul_f32 v[106:107], v[106:107], v[114:115] op_sel_hi:[1,0]
	v_pk_mul_f32 v[104:105], v[104:105], v[114:115] op_sel_hi:[1,0]
	v_pk_mul_f32 v[102:103], v[102:103], v[114:115] op_sel_hi:[1,0]
	v_pk_mul_f32 v[116:117], v[100:101], v[114:115] op_sel_hi:[1,0]
	v_pk_mul_f32 v[114:115], v[98:99], v[114:115] op_sel_hi:[1,0]
	v_mul_f32_e32 v98, 0x45800000, v118
	v_cndmask_b32_e64 v98, v118, v98, s[4:5]
	v_pk_mul_f32 v[100:101], v[128:129], v[98:99] op_sel_hi:[1,0]
	v_pk_mul_f32 v[118:119], v[126:127], v[98:99] op_sel_hi:[1,0]
	v_pk_mul_f32 v[120:121], v[174:175], v[98:99] op_sel_hi:[1,0]
	v_mul_f32_e32 v99, 0xbfb8aa3b, v110
	v_mul_f32_e32 v122, 0xbfb8aa3b, v111
	v_exp_f32_e32 v99, v99
	v_exp_f32_e32 v124, v122
	v_mul_f32_e32 v102, 0xbfb8aa3b, v102
	v_mul_f32_e32 v103, 0xbfb8aa3b, v103
	v_pk_mul_f32 v[122:123], v[172:173], v[98:99] op_sel_hi:[1,0]
	v_add_f32_e32 v98, 1.0, v99
	v_add_f32_e32 v99, 1.0, v124
	v_rcp_f32_e32 v98, v98
	v_rcp_f32_e32 v99, v99
	v_lshlrev_b32_e32 v124, 16, v176
	v_pk_mul_f32 v[118:119], v[118:119], v[124:125]
	v_exp_f32_e32 v102, v102
	v_pk_mul_f32 v[98:99], v[110:111], v[98:99]
	v_mul_f32_e32 v110, 0xbfb8aa3b, v112
	v_exp_f32_e32 v110, v110
	v_mul_f32_e32 v111, 0xbfb8aa3b, v113
	v_exp_f32_e32 v111, v111
	v_pk_mul_f32 v[98:99], v[118:119], v[98:99]
	v_lshlrev_b32_e32 v118, 16, v177
	v_cvt_pk_bf16_f32 v98, v98, v99
	v_add_f32_e32 v99, 1.0, v110
	v_rcp_f32_e32 v110, v99
	v_add_f32_e32 v99, 1.0, v111
	v_rcp_f32_e32 v111, v99
	v_and_b32_e32 v119, 0xffff0000, v177
	v_pk_mul_f32 v[100:101], v[100:101], v[118:119]
	v_mul_f32_e32 v99, 0xbfb8aa3b, v106
	v_pk_mul_f32 v[110:111], v[112:113], v[110:111]
	v_exp_f32_e32 v103, v103
	v_pk_mul_f32 v[100:101], v[100:101], v[110:111]
	v_exp_f32_e32 v110, v99
	v_mul_f32_e32 v99, 0xbfb8aa3b, v107
	v_exp_f32_e32 v111, v99
	v_cvt_pk_bf16_f32 v99, v100, v101
	v_add_f32_e32 v100, 1.0, v110
	v_rcp_f32_e32 v100, v100
	v_add_f32_e32 v101, 1.0, v111
	v_rcp_f32_e32 v101, v101
	v_lshlrev_b32_e32 v110, 16, v178
	v_and_b32_e32 v111, 0xffff0000, v178
	v_pk_mul_f32 v[110:111], v[122:123], v[110:111]
	v_pk_mul_f32 v[100:101], v[106:107], v[100:101]
	v_mul_f32_e32 v106, 0xbfb8aa3b, v108
	v_exp_f32_e32 v106, v106
	v_mul_f32_e32 v107, 0xbfb8aa3b, v109
	v_exp_f32_e32 v107, v107
	v_pk_mul_f32 v[100:101], v[110:111], v[100:101]
	v_lshlrev_b32_e32 v110, 16, v179
	v_cvt_pk_bf16_f32 v100, v100, v101
	v_add_f32_e32 v101, 1.0, v106
	v_rcp_f32_e32 v106, v101
	v_add_f32_e32 v101, 1.0, v107
	v_rcp_f32_e32 v107, v101
	v_and_b32_e32 v111, 0xffff0000, v179
	v_pk_mul_f32 v[110:111], v[120:121], v[110:111]
	v_or_b32_e32 v118, 32, v154
	v_pk_mul_f32 v[106:107], v[108:109], v[106:107]
	v_ashrrev_i32_e32 v119, 31, v118
	v_pk_mul_f32 v[106:107], v[110:111], v[106:107]
	v_lshlrev_b64 v[122:123], 11, v[118:119]
	v_cvt_pk_bf16_f32 v101, v106, v107
	global_store_dwordx4 v[180:181], v[98:101], off
	v_lshl_add_u64 v[124:125], v[152:153], 0, v[122:123]
	s_nop 0
	v_add_f32_e32 v98, 1.0, v102
	v_add_f32_e32 v99, 1.0, v103
	v_mul_f32_e32 v100, 0xbfb8aa3b, v104
	v_mul_f32_e32 v101, 0xbfb8aa3b, v105
	v_mul_f32_e32 v102, 0xbfb8aa3b, v114
	v_mul_f32_e32 v103, 0xbfb8aa3b, v115
	v_mul_f32_e32 v104, 0xbfb8aa3b, v116
	v_mul_f32_e32 v105, 0xbfb8aa3b, v117
	v_exp_f32_e32 v100, v100
	v_exp_f32_e32 v101, v101
	v_exp_f32_e32 v102, v102
	v_exp_f32_e32 v103, v103
	v_exp_f32_e32 v104, v104
	v_exp_f32_e32 v105, v105
	v_add_f32_e32 v100, 1.0, v100
	v_add_f32_e32 v101, 1.0, v101
	v_add_f32_e32 v102, 1.0, v102
	v_add_f32_e32 v103, 1.0, v103
	v_add_f32_e32 v104, 1.0, v104
	v_add_f32_e32 v105, 1.0, v105
	v_rcp_f32_e32 v98, v98
	v_rcp_f32_e32 v99, v99
	v_rcp_f32_e32 v100, v100
	v_rcp_f32_e32 v101, v101
	v_rcp_f32_e32 v102, v102
	v_rcp_f32_e32 v103, v103
	v_rcp_f32_e32 v104, v104
	v_rcp_f32_e32 v105, v105
	v_cvt_pk_bf16_f32 v98, v98, v99
	v_cvt_pk_bf16_f32 v99, v100, v101
	v_cvt_pk_bf16_f32 v100, v102, v103
	v_cvt_pk_bf16_f32 v101, v104, v105
	v_lshl_add_u64 v[102:103], v[150:151], 0, v[158:159]
	global_store_dwordx4 v[102:103], v[98:101], off
	v_lshlrev_b64 v[102:103], 8, v[118:119]
	v_lshl_add_u64 v[106:107], s[44:45], 0, v[102:103]
	v_lshlrev_b64 v[98:99], 6, v[118:119]
	v_lshl_add_u64 v[98:99], v[138:139], 0, v[98:99]
	global_load_dwordx4 v[98:101], v[98:99], off
	s_nop 0
	global_load_dwordx4 v[102:105], v[106:107], off
	s_nop 0
	global_load_dwordx4 v[106:109], v[106:107], off offset:16
	s_nop 0
	global_load_dwordx4 v[110:113], v[140:141], off
	global_load_dwordx4 v[114:117], v[140:141], off offset:16
	global_load_dwordx4 v[118:121], v[124:125], off
	s_waitcnt vmcnt(5)
	v_mov_b32_e32 v126, v99
	v_mov_b32_e32 v127, v100
	v_mov_b32_e32 v99, v101
	v_pk_add_f32 v[98:99], v[126:127], v[98:99]
	s_waitcnt vmcnt(4)
	v_mov_b32_e32 v126, v102
	v_add_f32_e32 v98, v98, v99
	ds_bpermute_b32 v99, v170, v98
	s_waitcnt vmcnt(3)
	v_mov_b32_e32 v127, v106
	v_mov_b32_e32 v106, v103
	v_pk_add_f32 v[102:103], v[126:127], v[106:107]
	v_mov_b32_e32 v106, v104
	s_waitcnt lgkmcnt(0)
	v_add_f32_e32 v99, v98, v99
	ds_bpermute_b32 v101, v155, v99
	v_mov_b32_e32 v107, v108
	v_mov_b32_e32 v108, v105
	v_pk_add_f32 v[104:105], v[106:107], v[108:109]
	s_waitcnt vmcnt(0)
	v_and_b32_e32 v109, 0xffff0000, v118
	v_pk_add_f32 v[102:103], v[102:103], v[104:105]
	s_nop 0
	v_mov_b32_e32 v98, v102
	v_mov_b32_e32 v100, v103
	s_waitcnt lgkmcnt(0)
	v_pk_add_f32 v[98:99], v[98:99], v[100:101]
	s_nop 0
	v_pk_fma_f32 v[98:99], v[98:99], s[18:19], v[156:157] op_sel_hi:[1,1,0]
	s_nop 0
	v_mul_f32_e32 v100, 0x4b800000, v99
	v_cmp_gt_f32_e32 vcc, s60, v99
	s_nop 1
	v_cndmask_b32_e32 v99, v99, v100, vcc
	v_rsq_f32_e32 v99, v99
	s_nop 0
	v_mul_f32_e32 v100, 0x45800000, v99
	v_cndmask_b32_e32 v100, v99, v100, vcc
	v_mul_f32_e32 v99, 0x4b800000, v98
	v_cmp_gt_f32_e32 vcc, s60, v98
	v_pk_mul_f32 v[96:97], v[96:97], v[100:101] op_sel_hi:[1,0]
	v_pk_mul_f32 v[94:95], v[94:95], v[100:101] op_sel_hi:[1,0]
	v_cndmask_b32_e32 v98, v98, v99, vcc
	v_rsq_f32_e32 v102, v98
	v_pk_mul_f32 v[92:93], v[92:93], v[100:101] op_sel_hi:[1,0]
	v_pk_mul_f32 v[90:91], v[90:91], v[100:101] op_sel_hi:[1,0]
	v_pk_mul_f32 v[88:89], v[88:89], v[100:101] op_sel_hi:[1,0]
	v_pk_mul_f32 v[86:87], v[86:87], v[100:101] op_sel_hi:[1,0]
	v_pk_mul_f32 v[98:99], v[84:85], v[100:101] op_sel_hi:[1,0]
	v_pk_mul_f32 v[100:101], v[82:83], v[100:101] op_sel_hi:[1,0]
	v_mul_f32_e32 v82, 0x45800000, v102
	v_cndmask_b32_e32 v82, v102, v82, vcc
	v_pk_mul_f32 v[84:85], v[112:113], v[82:83] op_sel_hi:[1,0]
	v_pk_mul_f32 v[102:103], v[110:111], v[82:83] op_sel_hi:[1,0]
	v_pk_mul_f32 v[104:105], v[116:117], v[82:83] op_sel_hi:[1,0]
	v_mul_f32_e32 v83, 0xbfb8aa3b, v94
	v_mul_f32_e32 v106, 0xbfb8aa3b, v95
	v_exp_f32_e32 v83, v83
	v_exp_f32_e32 v108, v106
	v_mul_f32_e32 v86, 0xbfb8aa3b, v86
	v_mul_f32_e32 v87, 0xbfb8aa3b, v87
	v_pk_mul_f32 v[106:107], v[114:115], v[82:83] op_sel_hi:[1,0]
	v_add_f32_e32 v82, 1.0, v83
	v_add_f32_e32 v83, 1.0, v108
	v_rcp_f32_e32 v82, v82
	v_rcp_f32_e32 v83, v83
	v_lshlrev_b32_e32 v108, 16, v118
	v_pk_mul_f32 v[102:103], v[102:103], v[108:109]
	v_exp_f32_e32 v86, v86
	v_pk_mul_f32 v[82:83], v[94:95], v[82:83]
	v_mul_f32_e32 v94, 0xbfb8aa3b, v96
	v_exp_f32_e32 v94, v94
	v_mul_f32_e32 v95, 0xbfb8aa3b, v97
	v_exp_f32_e32 v95, v95
	v_pk_mul_f32 v[82:83], v[102:103], v[82:83]
	v_lshlrev_b32_e32 v102, 16, v119
	v_cvt_pk_bf16_f32 v82, v82, v83
	v_add_f32_e32 v83, 1.0, v94
	v_rcp_f32_e32 v94, v83
	v_add_f32_e32 v83, 1.0, v95
	v_rcp_f32_e32 v95, v83
	v_and_b32_e32 v103, 0xffff0000, v119
	v_pk_mul_f32 v[84:85], v[84:85], v[102:103]
	v_mul_f32_e32 v83, 0xbfb8aa3b, v90
	v_pk_mul_f32 v[94:95], v[96:97], v[94:95]
	v_exp_f32_e32 v87, v87
	v_pk_mul_f32 v[84:85], v[84:85], v[94:95]
	v_exp_f32_e32 v94, v83
	v_mul_f32_e32 v83, 0xbfb8aa3b, v91
	v_exp_f32_e32 v95, v83
	v_cvt_pk_bf16_f32 v83, v84, v85
	v_add_f32_e32 v84, 1.0, v94
	v_rcp_f32_e32 v84, v84
	v_add_f32_e32 v85, 1.0, v95
	v_rcp_f32_e32 v85, v85
	v_lshlrev_b32_e32 v94, 16, v120
	v_and_b32_e32 v95, 0xffff0000, v120
	v_pk_mul_f32 v[94:95], v[106:107], v[94:95]
	v_pk_mul_f32 v[84:85], v[90:91], v[84:85]
	v_mul_f32_e32 v90, 0xbfb8aa3b, v92
	v_exp_f32_e32 v90, v90
	v_mul_f32_e32 v91, 0xbfb8aa3b, v93
	v_exp_f32_e32 v91, v91
	v_pk_mul_f32 v[84:85], v[94:95], v[84:85]
	v_lshlrev_b32_e32 v94, 16, v121
	v_cvt_pk_bf16_f32 v84, v84, v85
	v_add_f32_e32 v85, 1.0, v90
	v_rcp_f32_e32 v90, v85
	v_add_f32_e32 v85, 1.0, v91
	v_rcp_f32_e32 v91, v85
	v_and_b32_e32 v95, 0xffff0000, v121
	v_pk_mul_f32 v[94:95], v[104:105], v[94:95]
	v_or_b32_e32 v102, 48, v154
	v_pk_mul_f32 v[90:91], v[92:93], v[90:91]
	v_ashrrev_i32_e32 v103, 31, v102
	v_pk_mul_f32 v[90:91], v[94:95], v[90:91]
	v_lshlrev_b64 v[106:107], 11, v[102:103]
	v_cvt_pk_bf16_f32 v85, v90, v91
	global_store_dwordx4 v[124:125], v[82:85], off
	v_lshl_add_u64 v[108:109], v[152:153], 0, v[106:107]
	s_nop 0
	v_add_f32_e32 v82, 1.0, v86
	v_add_f32_e32 v83, 1.0, v87
	v_mul_f32_e32 v84, 0xbfb8aa3b, v88
	v_mul_f32_e32 v85, 0xbfb8aa3b, v89
	v_mul_f32_e32 v86, 0xbfb8aa3b, v100
	v_mul_f32_e32 v87, 0xbfb8aa3b, v101
	v_mul_f32_e32 v88, 0xbfb8aa3b, v98
	v_mul_f32_e32 v89, 0xbfb8aa3b, v99
	v_exp_f32_e32 v84, v84
	v_exp_f32_e32 v85, v85
	v_exp_f32_e32 v86, v86
	v_exp_f32_e32 v87, v87
	v_exp_f32_e32 v88, v88
	v_exp_f32_e32 v89, v89
	v_add_f32_e32 v84, 1.0, v84
	v_add_f32_e32 v85, 1.0, v85
	v_add_f32_e32 v86, 1.0, v86
	v_add_f32_e32 v87, 1.0, v87
	v_add_f32_e32 v88, 1.0, v88
	v_add_f32_e32 v89, 1.0, v89
	v_rcp_f32_e32 v82, v82
	v_rcp_f32_e32 v83, v83
	v_rcp_f32_e32 v84, v84
	v_rcp_f32_e32 v85, v85
	v_rcp_f32_e32 v86, v86
	v_rcp_f32_e32 v87, v87
	v_rcp_f32_e32 v88, v88
	v_rcp_f32_e32 v89, v89
	v_cvt_pk_bf16_f32 v82, v82, v83
	v_cvt_pk_bf16_f32 v83, v84, v85
	v_cvt_pk_bf16_f32 v84, v86, v87
	v_cvt_pk_bf16_f32 v85, v88, v89
	v_lshl_add_u64 v[86:87], v[150:151], 0, v[122:123]
	global_store_dwordx4 v[86:87], v[82:85], off
	v_lshlrev_b64 v[86:87], 8, v[102:103]
	v_lshl_add_u64 v[90:91], s[44:45], 0, v[86:87]
	v_lshlrev_b64 v[82:83], 6, v[102:103]
	v_lshl_add_u64 v[82:83], v[138:139], 0, v[82:83]
	global_load_dwordx4 v[82:85], v[82:83], off
	s_nop 0
	global_load_dwordx4 v[86:89], v[90:91], off
	s_nop 0
	global_load_dwordx4 v[90:93], v[90:91], off offset:16
	s_nop 0
	global_load_dwordx4 v[94:97], v[140:141], off
	global_load_dwordx4 v[98:101], v[140:141], off offset:16
	global_load_dwordx4 v[102:105], v[108:109], off
	s_waitcnt vmcnt(5)
	v_mov_b32_e32 v110, v83
	v_mov_b32_e32 v111, v84
	v_mov_b32_e32 v83, v85
	v_pk_add_f32 v[82:83], v[110:111], v[82:83]
	s_waitcnt vmcnt(4)
	v_mov_b32_e32 v110, v86
	v_add_f32_e32 v82, v82, v83
	ds_bpermute_b32 v83, v170, v82
	s_waitcnt vmcnt(3)
	v_mov_b32_e32 v111, v90
	v_mov_b32_e32 v90, v87
	v_pk_add_f32 v[86:87], v[110:111], v[90:91]
	v_mov_b32_e32 v90, v88
	s_waitcnt lgkmcnt(0)
	v_add_f32_e32 v83, v82, v83
	ds_bpermute_b32 v85, v155, v83
	v_mov_b32_e32 v91, v92
	v_mov_b32_e32 v92, v89
	v_pk_add_f32 v[88:89], v[90:91], v[92:93]
	s_waitcnt vmcnt(0)
	v_and_b32_e32 v93, 0xffff0000, v102
	v_pk_add_f32 v[86:87], v[86:87], v[88:89]
	s_nop 0
	v_mov_b32_e32 v82, v86
	v_mov_b32_e32 v84, v87
	s_waitcnt lgkmcnt(0)
	v_pk_add_f32 v[82:83], v[82:83], v[84:85]
	s_nop 0
	v_pk_fma_f32 v[82:83], v[82:83], s[18:19], v[156:157] op_sel_hi:[1,1,0]
	s_nop 0
	v_mul_f32_e32 v84, 0x4b800000, v83
	v_cmp_gt_f32_e32 vcc, s60, v83
	s_nop 1
	v_cndmask_b32_e32 v83, v83, v84, vcc
	v_rsq_f32_e32 v83, v83
	s_nop 0
	v_mul_f32_e32 v84, 0x45800000, v83
	v_cndmask_b32_e32 v84, v83, v84, vcc
	v_mul_f32_e32 v83, 0x4b800000, v82
	v_cmp_gt_f32_e32 vcc, s60, v82
	v_pk_mul_f32 v[80:81], v[80:81], v[84:85] op_sel_hi:[1,0]
	v_pk_mul_f32 v[78:79], v[78:79], v[84:85] op_sel_hi:[1,0]
	v_cndmask_b32_e32 v82, v82, v83, vcc
	v_rsq_f32_e32 v86, v82
	v_pk_mul_f32 v[76:77], v[76:77], v[84:85] op_sel_hi:[1,0]
	v_pk_mul_f32 v[74:75], v[74:75], v[84:85] op_sel_hi:[1,0]
	v_pk_mul_f32 v[72:73], v[72:73], v[84:85] op_sel_hi:[1,0]
	v_pk_mul_f32 v[70:71], v[70:71], v[84:85] op_sel_hi:[1,0]
	v_pk_mul_f32 v[82:83], v[68:69], v[84:85] op_sel_hi:[1,0]
	v_pk_mul_f32 v[84:85], v[66:67], v[84:85] op_sel_hi:[1,0]
	v_mul_f32_e32 v66, 0x45800000, v86
	v_cndmask_b32_e32 v66, v86, v66, vcc
	v_pk_mul_f32 v[68:69], v[96:97], v[66:67] op_sel_hi:[1,0]
	v_pk_mul_f32 v[86:87], v[94:95], v[66:67] op_sel_hi:[1,0]
	v_pk_mul_f32 v[88:89], v[100:101], v[66:67] op_sel_hi:[1,0]
	v_mul_f32_e32 v67, 0xbfb8aa3b, v78
	v_mul_f32_e32 v90, 0xbfb8aa3b, v79
	v_exp_f32_e32 v67, v67
	v_exp_f32_e32 v92, v90
	v_mul_f32_e32 v70, 0xbfb8aa3b, v70
	v_mul_f32_e32 v71, 0xbfb8aa3b, v71
	v_pk_mul_f32 v[90:91], v[98:99], v[66:67] op_sel_hi:[1,0]
	v_add_f32_e32 v66, 1.0, v67
	v_add_f32_e32 v67, 1.0, v92
	v_rcp_f32_e32 v66, v66
	v_rcp_f32_e32 v67, v67
	v_lshlrev_b32_e32 v92, 16, v102
	v_pk_mul_f32 v[86:87], v[86:87], v[92:93]
	v_exp_f32_e32 v70, v70
	v_pk_mul_f32 v[66:67], v[78:79], v[66:67]
	v_mul_f32_e32 v78, 0xbfb8aa3b, v80
	v_exp_f32_e32 v78, v78
	v_mul_f32_e32 v79, 0xbfb8aa3b, v81
	v_exp_f32_e32 v79, v79
	v_pk_mul_f32 v[66:67], v[86:87], v[66:67]
	v_lshlrev_b32_e32 v86, 16, v103
	v_cvt_pk_bf16_f32 v66, v66, v67
	v_add_f32_e32 v67, 1.0, v78
	v_rcp_f32_e32 v78, v67
	v_add_f32_e32 v67, 1.0, v79
	v_rcp_f32_e32 v79, v67
	v_and_b32_e32 v87, 0xffff0000, v103
	v_pk_mul_f32 v[68:69], v[68:69], v[86:87]
	v_mul_f32_e32 v67, 0xbfb8aa3b, v74
	v_pk_mul_f32 v[78:79], v[80:81], v[78:79]
	v_exp_f32_e32 v71, v71
	v_pk_mul_f32 v[68:69], v[68:69], v[78:79]
	v_exp_f32_e32 v78, v67
	v_mul_f32_e32 v67, 0xbfb8aa3b, v75
	v_exp_f32_e32 v79, v67
	v_cvt_pk_bf16_f32 v67, v68, v69
	v_add_f32_e32 v68, 1.0, v78
	v_rcp_f32_e32 v68, v68
	v_add_f32_e32 v69, 1.0, v79
	v_rcp_f32_e32 v69, v69
	v_lshlrev_b32_e32 v78, 16, v104
	v_and_b32_e32 v79, 0xffff0000, v104
	v_pk_mul_f32 v[78:79], v[90:91], v[78:79]
	v_pk_mul_f32 v[68:69], v[74:75], v[68:69]
	v_mul_f32_e32 v74, 0xbfb8aa3b, v76
	v_exp_f32_e32 v74, v74
	v_mul_f32_e32 v75, 0xbfb8aa3b, v77
	v_exp_f32_e32 v75, v75
	v_pk_mul_f32 v[68:69], v[78:79], v[68:69]
	v_lshlrev_b32_e32 v78, 16, v105
	v_cvt_pk_bf16_f32 v68, v68, v69
	v_add_f32_e32 v69, 1.0, v74
	v_rcp_f32_e32 v74, v69
	v_add_f32_e32 v69, 1.0, v75
	v_rcp_f32_e32 v75, v69
	v_and_b32_e32 v79, 0xffff0000, v105
	v_pk_mul_f32 v[78:79], v[88:89], v[78:79]
	v_add_u32_e32 v86, 0x80, v154
	v_pk_mul_f32 v[74:75], v[76:77], v[74:75]
	v_ashrrev_i32_e32 v87, 31, v86
	v_pk_mul_f32 v[74:75], v[78:79], v[74:75]
	v_lshlrev_b64 v[90:91], 11, v[86:87]
	v_cvt_pk_bf16_f32 v69, v74, v75
	global_store_dwordx4 v[108:109], v[66:69], off
	v_lshl_add_u64 v[92:93], v[152:153], 0, v[90:91]
	s_nop 0
	v_add_f32_e32 v66, 1.0, v70
	v_add_f32_e32 v67, 1.0, v71
	v_mul_f32_e32 v68, 0xbfb8aa3b, v72
	v_mul_f32_e32 v69, 0xbfb8aa3b, v73
	v_mul_f32_e32 v70, 0xbfb8aa3b, v84
	v_mul_f32_e32 v71, 0xbfb8aa3b, v85
	v_mul_f32_e32 v72, 0xbfb8aa3b, v82
	v_mul_f32_e32 v73, 0xbfb8aa3b, v83
	v_exp_f32_e32 v68, v68
	v_exp_f32_e32 v69, v69
	v_exp_f32_e32 v70, v70
	v_exp_f32_e32 v71, v71
	v_exp_f32_e32 v72, v72
	v_exp_f32_e32 v73, v73
	v_add_f32_e32 v68, 1.0, v68
	v_add_f32_e32 v69, 1.0, v69
	v_add_f32_e32 v70, 1.0, v70
	v_add_f32_e32 v71, 1.0, v71
	v_add_f32_e32 v72, 1.0, v72
	v_add_f32_e32 v73, 1.0, v73
	v_rcp_f32_e32 v66, v66
	v_rcp_f32_e32 v67, v67
	v_rcp_f32_e32 v68, v68
	v_rcp_f32_e32 v69, v69
	v_rcp_f32_e32 v70, v70
	v_rcp_f32_e32 v71, v71
	v_rcp_f32_e32 v72, v72
	v_rcp_f32_e32 v73, v73
	v_cvt_pk_bf16_f32 v66, v66, v67
	v_cvt_pk_bf16_f32 v67, v68, v69
	v_cvt_pk_bf16_f32 v68, v70, v71
	v_cvt_pk_bf16_f32 v69, v72, v73
	v_lshl_add_u64 v[70:71], v[150:151], 0, v[106:107]
	global_store_dwordx4 v[70:71], v[66:69], off
	v_lshlrev_b64 v[70:71], 8, v[86:87]
	v_lshl_add_u64 v[74:75], s[44:45], 0, v[70:71]
	v_lshlrev_b64 v[66:67], 6, v[86:87]
	v_lshl_add_u64 v[66:67], v[138:139], 0, v[66:67]
	global_load_dwordx4 v[66:69], v[66:67], off
	s_nop 0
	global_load_dwordx4 v[70:73], v[74:75], off
	s_nop 0
	global_load_dwordx4 v[74:77], v[74:75], off offset:16
	s_nop 0
	global_load_dwordx4 v[78:81], v[140:141], off
	global_load_dwordx4 v[82:85], v[140:141], off offset:16
	global_load_dwordx4 v[86:89], v[92:93], off
	s_waitcnt vmcnt(5)
	v_mov_b32_e32 v94, v67
	v_mov_b32_e32 v95, v68
	v_mov_b32_e32 v67, v69
	v_pk_add_f32 v[66:67], v[94:95], v[66:67]
	s_waitcnt vmcnt(4)
	v_mov_b32_e32 v94, v70
	v_add_f32_e32 v66, v66, v67
	ds_bpermute_b32 v67, v170, v66
	s_waitcnt vmcnt(3)
	v_mov_b32_e32 v95, v74
	v_mov_b32_e32 v74, v71
	v_pk_add_f32 v[70:71], v[94:95], v[74:75]
	v_mov_b32_e32 v74, v72
	s_waitcnt lgkmcnt(0)
	v_add_f32_e32 v67, v66, v67
	ds_bpermute_b32 v69, v155, v67
	v_mov_b32_e32 v75, v76
	v_mov_b32_e32 v76, v73
	v_pk_add_f32 v[72:73], v[74:75], v[76:77]
	s_waitcnt vmcnt(0)
	v_and_b32_e32 v77, 0xffff0000, v86
	v_pk_add_f32 v[70:71], v[70:71], v[72:73]
	s_nop 0
	v_mov_b32_e32 v66, v70
	v_mov_b32_e32 v68, v71
	s_waitcnt lgkmcnt(0)
	v_pk_add_f32 v[66:67], v[66:67], v[68:69]
	s_nop 0
	v_pk_fma_f32 v[66:67], v[66:67], s[18:19], v[156:157] op_sel_hi:[1,1,0]
	s_nop 0
	v_mul_f32_e32 v68, 0x4b800000, v67
	v_cmp_gt_f32_e32 vcc, s60, v67
	s_nop 1
	v_cndmask_b32_e32 v67, v67, v68, vcc
	v_rsq_f32_e32 v67, v67
	s_nop 0
	v_mul_f32_e32 v68, 0x45800000, v67
	v_cndmask_b32_e32 v68, v67, v68, vcc
	v_mul_f32_e32 v67, 0x4b800000, v66
	v_cmp_gt_f32_e32 vcc, s60, v66
	v_pk_mul_f32 v[64:65], v[64:65], v[68:69] op_sel_hi:[1,0]
	v_pk_mul_f32 v[62:63], v[62:63], v[68:69] op_sel_hi:[1,0]
	v_cndmask_b32_e32 v66, v66, v67, vcc
	v_rsq_f32_e32 v70, v66
	v_pk_mul_f32 v[60:61], v[60:61], v[68:69] op_sel_hi:[1,0]
	v_pk_mul_f32 v[58:59], v[58:59], v[68:69] op_sel_hi:[1,0]
	v_pk_mul_f32 v[56:57], v[56:57], v[68:69] op_sel_hi:[1,0]
	v_pk_mul_f32 v[54:55], v[54:55], v[68:69] op_sel_hi:[1,0]
	v_pk_mul_f32 v[66:67], v[52:53], v[68:69] op_sel_hi:[1,0]
	v_pk_mul_f32 v[68:69], v[50:51], v[68:69] op_sel_hi:[1,0]
	v_mul_f32_e32 v50, 0x45800000, v70
	v_cndmask_b32_e32 v50, v70, v50, vcc
	v_pk_mul_f32 v[52:53], v[80:81], v[50:51] op_sel_hi:[1,0]
	v_pk_mul_f32 v[70:71], v[78:79], v[50:51] op_sel_hi:[1,0]
	v_pk_mul_f32 v[72:73], v[84:85], v[50:51] op_sel_hi:[1,0]
	v_mul_f32_e32 v51, 0xbfb8aa3b, v62
	v_mul_f32_e32 v74, 0xbfb8aa3b, v63
	v_exp_f32_e32 v51, v51
	v_exp_f32_e32 v76, v74
	v_mul_f32_e32 v54, 0xbfb8aa3b, v54
	v_mul_f32_e32 v55, 0xbfb8aa3b, v55
	v_pk_mul_f32 v[74:75], v[82:83], v[50:51] op_sel_hi:[1,0]
	v_add_f32_e32 v50, 1.0, v51
	v_add_f32_e32 v51, 1.0, v76
	v_rcp_f32_e32 v50, v50
	v_rcp_f32_e32 v51, v51
	v_lshlrev_b32_e32 v76, 16, v86
	v_pk_mul_f32 v[70:71], v[70:71], v[76:77]
	v_exp_f32_e32 v54, v54
	v_pk_mul_f32 v[50:51], v[62:63], v[50:51]
	v_mul_f32_e32 v62, 0xbfb8aa3b, v64
	v_exp_f32_e32 v62, v62
	v_mul_f32_e32 v63, 0xbfb8aa3b, v65
	v_exp_f32_e32 v63, v63
	v_pk_mul_f32 v[50:51], v[70:71], v[50:51]
	v_lshlrev_b32_e32 v70, 16, v87
	v_cvt_pk_bf16_f32 v50, v50, v51
	v_add_f32_e32 v51, 1.0, v62
	v_rcp_f32_e32 v62, v51
	v_add_f32_e32 v51, 1.0, v63
	v_rcp_f32_e32 v63, v51
	v_and_b32_e32 v71, 0xffff0000, v87
	v_pk_mul_f32 v[52:53], v[52:53], v[70:71]
	v_mul_f32_e32 v51, 0xbfb8aa3b, v58
	v_pk_mul_f32 v[62:63], v[64:65], v[62:63]
	v_exp_f32_e32 v55, v55
	v_pk_mul_f32 v[52:53], v[52:53], v[62:63]
	v_exp_f32_e32 v62, v51
	v_mul_f32_e32 v51, 0xbfb8aa3b, v59
	v_exp_f32_e32 v63, v51
	v_cvt_pk_bf16_f32 v51, v52, v53
	v_add_f32_e32 v52, 1.0, v62
	v_rcp_f32_e32 v52, v52
	v_add_f32_e32 v53, 1.0, v63
	v_rcp_f32_e32 v53, v53
	v_lshlrev_b32_e32 v62, 16, v88
	v_and_b32_e32 v63, 0xffff0000, v88
	v_pk_mul_f32 v[62:63], v[74:75], v[62:63]
	v_pk_mul_f32 v[52:53], v[58:59], v[52:53]
	v_mul_f32_e32 v58, 0xbfb8aa3b, v60
	v_exp_f32_e32 v58, v58
	v_mul_f32_e32 v59, 0xbfb8aa3b, v61
	v_exp_f32_e32 v59, v59
	v_pk_mul_f32 v[52:53], v[62:63], v[52:53]
	v_lshlrev_b32_e32 v62, 16, v89
	v_cvt_pk_bf16_f32 v52, v52, v53
	v_add_f32_e32 v53, 1.0, v58
	v_rcp_f32_e32 v58, v53
	v_add_f32_e32 v53, 1.0, v59
	v_rcp_f32_e32 v59, v53
	v_and_b32_e32 v63, 0xffff0000, v89
	v_pk_mul_f32 v[62:63], v[72:73], v[62:63]
	v_add_u32_e32 v70, 0x90, v154
	v_pk_mul_f32 v[58:59], v[60:61], v[58:59]
	v_ashrrev_i32_e32 v71, 31, v70
	v_pk_mul_f32 v[58:59], v[62:63], v[58:59]
	v_lshlrev_b64 v[74:75], 11, v[70:71]
	v_cvt_pk_bf16_f32 v53, v58, v59
	global_store_dwordx4 v[92:93], v[50:53], off
	v_lshl_add_u64 v[76:77], v[152:153], 0, v[74:75]
	s_nop 0
	v_add_f32_e32 v50, 1.0, v54
	v_add_f32_e32 v51, 1.0, v55
	v_mul_f32_e32 v52, 0xbfb8aa3b, v56
	v_mul_f32_e32 v53, 0xbfb8aa3b, v57
	v_mul_f32_e32 v54, 0xbfb8aa3b, v68
	v_mul_f32_e32 v55, 0xbfb8aa3b, v69
	v_mul_f32_e32 v56, 0xbfb8aa3b, v66
	v_mul_f32_e32 v57, 0xbfb8aa3b, v67
	v_exp_f32_e32 v52, v52
	v_exp_f32_e32 v53, v53
	v_exp_f32_e32 v54, v54
	v_exp_f32_e32 v55, v55
	v_exp_f32_e32 v56, v56
	v_exp_f32_e32 v57, v57
	v_add_f32_e32 v52, 1.0, v52
	v_add_f32_e32 v53, 1.0, v53
	v_add_f32_e32 v54, 1.0, v54
	v_add_f32_e32 v55, 1.0, v55
	v_add_f32_e32 v56, 1.0, v56
	v_add_f32_e32 v57, 1.0, v57
	v_rcp_f32_e32 v50, v50
	v_rcp_f32_e32 v51, v51
	v_rcp_f32_e32 v52, v52
	v_rcp_f32_e32 v53, v53
	v_rcp_f32_e32 v54, v54
	v_rcp_f32_e32 v55, v55
	v_rcp_f32_e32 v56, v56
	v_rcp_f32_e32 v57, v57
	v_cvt_pk_bf16_f32 v50, v50, v51
	v_cvt_pk_bf16_f32 v51, v52, v53
	v_cvt_pk_bf16_f32 v52, v54, v55
	v_cvt_pk_bf16_f32 v53, v56, v57
	v_lshl_add_u64 v[54:55], v[150:151], 0, v[90:91]
	global_store_dwordx4 v[54:55], v[50:53], off
	v_lshlrev_b64 v[54:55], 8, v[70:71]
	v_lshl_add_u64 v[58:59], s[44:45], 0, v[54:55]
	v_lshlrev_b64 v[50:51], 6, v[70:71]
	v_lshl_add_u64 v[50:51], v[138:139], 0, v[50:51]
	global_load_dwordx4 v[50:53], v[50:51], off
	s_nop 0
	global_load_dwordx4 v[54:57], v[58:59], off
	s_nop 0
	global_load_dwordx4 v[58:61], v[58:59], off offset:16
	s_nop 0
	global_load_dwordx4 v[62:65], v[140:141], off
	global_load_dwordx4 v[66:69], v[140:141], off offset:16
	global_load_dwordx4 v[70:73], v[76:77], off
	s_waitcnt vmcnt(5)
	v_mov_b32_e32 v78, v51
	v_mov_b32_e32 v79, v52
	v_mov_b32_e32 v51, v53
	v_pk_add_f32 v[50:51], v[78:79], v[50:51]
	s_waitcnt vmcnt(4)
	v_mov_b32_e32 v78, v54
	v_add_f32_e32 v50, v50, v51
	ds_bpermute_b32 v51, v170, v50
	s_waitcnt vmcnt(3)
	v_mov_b32_e32 v79, v58
	v_mov_b32_e32 v58, v55
	v_pk_add_f32 v[54:55], v[78:79], v[58:59]
	v_mov_b32_e32 v58, v56
	s_waitcnt lgkmcnt(0)
	v_add_f32_e32 v51, v50, v51
	ds_bpermute_b32 v53, v155, v51
	v_mov_b32_e32 v59, v60
	v_mov_b32_e32 v60, v57
	v_pk_add_f32 v[56:57], v[58:59], v[60:61]
	s_waitcnt vmcnt(0)
	v_and_b32_e32 v61, 0xffff0000, v70
	v_pk_add_f32 v[54:55], v[54:55], v[56:57]
	s_nop 0
	v_mov_b32_e32 v50, v54
	v_mov_b32_e32 v52, v55
	s_waitcnt lgkmcnt(0)
	v_pk_add_f32 v[50:51], v[50:51], v[52:53]
	s_nop 0
	v_pk_fma_f32 v[50:51], v[50:51], s[18:19], v[156:157] op_sel_hi:[1,1,0]
	s_nop 0
	v_mul_f32_e32 v52, 0x4b800000, v51
	v_cmp_gt_f32_e32 vcc, s60, v51
	s_nop 1
	v_cndmask_b32_e32 v51, v51, v52, vcc
	v_rsq_f32_e32 v51, v51
	s_nop 0
	v_mul_f32_e32 v52, 0x45800000, v51
	v_cndmask_b32_e32 v52, v51, v52, vcc
	v_mul_f32_e32 v51, 0x4b800000, v50
	v_cmp_gt_f32_e32 vcc, s60, v50
	v_pk_mul_f32 v[48:49], v[48:49], v[52:53] op_sel_hi:[1,0]
	v_pk_mul_f32 v[46:47], v[46:47], v[52:53] op_sel_hi:[1,0]
	v_cndmask_b32_e32 v50, v50, v51, vcc
	v_rsq_f32_e32 v54, v50
	v_pk_mul_f32 v[44:45], v[44:45], v[52:53] op_sel_hi:[1,0]
	v_pk_mul_f32 v[42:43], v[42:43], v[52:53] op_sel_hi:[1,0]
	v_pk_mul_f32 v[40:41], v[40:41], v[52:53] op_sel_hi:[1,0]
	v_pk_mul_f32 v[38:39], v[38:39], v[52:53] op_sel_hi:[1,0]
	v_pk_mul_f32 v[50:51], v[36:37], v[52:53] op_sel_hi:[1,0]
	v_pk_mul_f32 v[52:53], v[34:35], v[52:53] op_sel_hi:[1,0]
	v_mul_f32_e32 v34, 0x45800000, v54
	v_cndmask_b32_e32 v34, v54, v34, vcc
	v_pk_mul_f32 v[36:37], v[64:65], v[34:35] op_sel_hi:[1,0]
	v_pk_mul_f32 v[54:55], v[62:63], v[34:35] op_sel_hi:[1,0]
	v_pk_mul_f32 v[56:57], v[68:69], v[34:35] op_sel_hi:[1,0]
	v_mul_f32_e32 v35, 0xbfb8aa3b, v46
	v_mul_f32_e32 v58, 0xbfb8aa3b, v47
	v_exp_f32_e32 v35, v35
	v_exp_f32_e32 v60, v58
	v_mul_f32_e32 v38, 0xbfb8aa3b, v38
	v_mul_f32_e32 v39, 0xbfb8aa3b, v39
	v_pk_mul_f32 v[58:59], v[66:67], v[34:35] op_sel_hi:[1,0]
	v_add_f32_e32 v34, 1.0, v35
	v_add_f32_e32 v35, 1.0, v60
	v_rcp_f32_e32 v34, v34
	v_rcp_f32_e32 v35, v35
	v_lshlrev_b32_e32 v60, 16, v70
	v_pk_mul_f32 v[54:55], v[54:55], v[60:61]
	v_exp_f32_e32 v38, v38
	v_pk_mul_f32 v[34:35], v[46:47], v[34:35]
	v_mul_f32_e32 v46, 0xbfb8aa3b, v48
	v_exp_f32_e32 v46, v46
	v_mul_f32_e32 v47, 0xbfb8aa3b, v49
	v_exp_f32_e32 v47, v47
	v_pk_mul_f32 v[34:35], v[54:55], v[34:35]
	v_lshlrev_b32_e32 v54, 16, v71
	v_cvt_pk_bf16_f32 v34, v34, v35
	v_add_f32_e32 v35, 1.0, v46
	v_rcp_f32_e32 v46, v35
	v_add_f32_e32 v35, 1.0, v47
	v_rcp_f32_e32 v47, v35
	v_and_b32_e32 v55, 0xffff0000, v71
	v_pk_mul_f32 v[36:37], v[36:37], v[54:55]
	v_mul_f32_e32 v35, 0xbfb8aa3b, v42
	v_pk_mul_f32 v[46:47], v[48:49], v[46:47]
	v_exp_f32_e32 v39, v39
	v_pk_mul_f32 v[36:37], v[36:37], v[46:47]
	v_exp_f32_e32 v46, v35
	v_mul_f32_e32 v35, 0xbfb8aa3b, v43
	v_exp_f32_e32 v47, v35
	v_cvt_pk_bf16_f32 v35, v36, v37
	v_add_f32_e32 v36, 1.0, v46
	v_rcp_f32_e32 v36, v36
	v_add_f32_e32 v37, 1.0, v47
	v_rcp_f32_e32 v37, v37
	v_lshlrev_b32_e32 v46, 16, v72
	v_and_b32_e32 v47, 0xffff0000, v72
	v_pk_mul_f32 v[46:47], v[58:59], v[46:47]
	v_pk_mul_f32 v[36:37], v[42:43], v[36:37]
	v_mul_f32_e32 v42, 0xbfb8aa3b, v44
	v_exp_f32_e32 v42, v42
	v_mul_f32_e32 v43, 0xbfb8aa3b, v45
	v_exp_f32_e32 v43, v43
	v_pk_mul_f32 v[36:37], v[46:47], v[36:37]
	v_lshlrev_b32_e32 v46, 16, v73
	v_cvt_pk_bf16_f32 v36, v36, v37
	v_add_f32_e32 v37, 1.0, v42
	v_rcp_f32_e32 v42, v37
	v_add_f32_e32 v37, 1.0, v43
	v_rcp_f32_e32 v43, v37
	v_and_b32_e32 v47, 0xffff0000, v73
	v_pk_mul_f32 v[46:47], v[56:57], v[46:47]
	v_add_u32_e32 v54, 0xa0, v154
	v_pk_mul_f32 v[42:43], v[44:45], v[42:43]
	v_ashrrev_i32_e32 v55, 31, v54
	v_pk_mul_f32 v[42:43], v[46:47], v[42:43]
	v_lshlrev_b64 v[58:59], 11, v[54:55]
	v_cvt_pk_bf16_f32 v37, v42, v43
	global_store_dwordx4 v[76:77], v[34:37], off
	v_lshl_add_u64 v[60:61], v[152:153], 0, v[58:59]
	s_nop 0
	v_add_f32_e32 v34, 1.0, v38
	v_add_f32_e32 v35, 1.0, v39
	v_mul_f32_e32 v36, 0xbfb8aa3b, v40
	v_mul_f32_e32 v37, 0xbfb8aa3b, v41
	v_mul_f32_e32 v38, 0xbfb8aa3b, v52
	v_mul_f32_e32 v39, 0xbfb8aa3b, v53
	v_mul_f32_e32 v40, 0xbfb8aa3b, v50
	v_mul_f32_e32 v41, 0xbfb8aa3b, v51
	v_exp_f32_e32 v36, v36
	v_exp_f32_e32 v37, v37
	v_exp_f32_e32 v38, v38
	v_exp_f32_e32 v39, v39
	v_exp_f32_e32 v40, v40
	v_exp_f32_e32 v41, v41
	v_add_f32_e32 v36, 1.0, v36
	v_add_f32_e32 v37, 1.0, v37
	v_add_f32_e32 v38, 1.0, v38
	v_add_f32_e32 v39, 1.0, v39
	v_add_f32_e32 v40, 1.0, v40
	v_add_f32_e32 v41, 1.0, v41
	v_rcp_f32_e32 v34, v34
	v_rcp_f32_e32 v35, v35
	v_rcp_f32_e32 v36, v36
	v_rcp_f32_e32 v37, v37
	v_rcp_f32_e32 v38, v38
	v_rcp_f32_e32 v39, v39
	v_rcp_f32_e32 v40, v40
	v_rcp_f32_e32 v41, v41
	v_cvt_pk_bf16_f32 v34, v34, v35
	v_cvt_pk_bf16_f32 v35, v36, v37
	v_cvt_pk_bf16_f32 v36, v38, v39
	v_cvt_pk_bf16_f32 v37, v40, v41
	v_lshl_add_u64 v[38:39], v[150:151], 0, v[74:75]
	global_store_dwordx4 v[38:39], v[34:37], off
	v_lshlrev_b64 v[38:39], 8, v[54:55]
	v_lshl_add_u64 v[42:43], s[44:45], 0, v[38:39]
	v_lshlrev_b64 v[34:35], 6, v[54:55]
	v_lshl_add_u64 v[34:35], v[138:139], 0, v[34:35]
	global_load_dwordx4 v[34:37], v[34:35], off
	s_nop 0
	global_load_dwordx4 v[38:41], v[42:43], off
	s_nop 0
	global_load_dwordx4 v[42:45], v[42:43], off offset:16
	s_nop 0
	global_load_dwordx4 v[46:49], v[140:141], off
	global_load_dwordx4 v[50:53], v[140:141], off offset:16
	global_load_dwordx4 v[54:57], v[60:61], off
	s_waitcnt vmcnt(5)
	v_mov_b32_e32 v62, v35
	v_mov_b32_e32 v63, v36
	v_mov_b32_e32 v35, v37
	v_pk_add_f32 v[34:35], v[62:63], v[34:35]
	s_waitcnt vmcnt(4)
	v_mov_b32_e32 v62, v38
	v_add_f32_e32 v34, v34, v35
	ds_bpermute_b32 v35, v170, v34
	s_waitcnt vmcnt(3)
	v_mov_b32_e32 v63, v42
	v_mov_b32_e32 v42, v39
	v_pk_add_f32 v[38:39], v[62:63], v[42:43]
	v_mov_b32_e32 v42, v40
	s_waitcnt lgkmcnt(0)
	v_add_f32_e32 v35, v34, v35
	ds_bpermute_b32 v37, v155, v35
	v_mov_b32_e32 v43, v44
	v_mov_b32_e32 v44, v41
	v_pk_add_f32 v[40:41], v[42:43], v[44:45]
	s_waitcnt vmcnt(0)
	v_and_b32_e32 v45, 0xffff0000, v54
	v_pk_add_f32 v[38:39], v[38:39], v[40:41]
	s_nop 0
	v_mov_b32_e32 v34, v38
	v_mov_b32_e32 v36, v39
	s_waitcnt lgkmcnt(0)
	v_pk_add_f32 v[34:35], v[34:35], v[36:37]
	s_nop 0
	v_pk_fma_f32 v[34:35], v[34:35], s[18:19], v[156:157] op_sel_hi:[1,1,0]
	s_nop 0
	v_mul_f32_e32 v36, 0x4b800000, v35
	v_cmp_gt_f32_e32 vcc, s60, v35
	s_nop 1
	v_cndmask_b32_e32 v35, v35, v36, vcc
	v_rsq_f32_e32 v35, v35
	s_nop 0
	v_mul_f32_e32 v36, 0x45800000, v35
	v_cndmask_b32_e32 v36, v35, v36, vcc
	v_mul_f32_e32 v35, 0x4b800000, v34
	v_cmp_gt_f32_e32 vcc, s60, v34
	v_pk_mul_f32 v[32:33], v[32:33], v[36:37] op_sel_hi:[1,0]
	v_pk_mul_f32 v[30:31], v[30:31], v[36:37] op_sel_hi:[1,0]
	v_cndmask_b32_e32 v34, v34, v35, vcc
	v_rsq_f32_e32 v38, v34
	v_pk_mul_f32 v[28:29], v[28:29], v[36:37] op_sel_hi:[1,0]
	v_pk_mul_f32 v[26:27], v[26:27], v[36:37] op_sel_hi:[1,0]
	v_pk_mul_f32 v[24:25], v[24:25], v[36:37] op_sel_hi:[1,0]
	v_pk_mul_f32 v[22:23], v[22:23], v[36:37] op_sel_hi:[1,0]
	v_pk_mul_f32 v[34:35], v[20:21], v[36:37] op_sel_hi:[1,0]
	v_pk_mul_f32 v[36:37], v[18:19], v[36:37] op_sel_hi:[1,0]
	v_mul_f32_e32 v18, 0x45800000, v38
	v_cndmask_b32_e32 v18, v38, v18, vcc
	v_pk_mul_f32 v[20:21], v[48:49], v[18:19] op_sel_hi:[1,0]
	v_pk_mul_f32 v[38:39], v[46:47], v[18:19] op_sel_hi:[1,0]
	v_pk_mul_f32 v[40:41], v[52:53], v[18:19] op_sel_hi:[1,0]
	v_mul_f32_e32 v19, 0xbfb8aa3b, v30
	v_mul_f32_e32 v42, 0xbfb8aa3b, v31
	v_exp_f32_e32 v19, v19
	v_exp_f32_e32 v44, v42
	v_mul_f32_e32 v22, 0xbfb8aa3b, v22
	v_mul_f32_e32 v23, 0xbfb8aa3b, v23
	v_pk_mul_f32 v[42:43], v[50:51], v[18:19] op_sel_hi:[1,0]
	v_add_f32_e32 v18, 1.0, v19
	v_add_f32_e32 v19, 1.0, v44
	v_rcp_f32_e32 v18, v18
	v_rcp_f32_e32 v19, v19
	v_lshlrev_b32_e32 v44, 16, v54
	v_pk_mul_f32 v[38:39], v[38:39], v[44:45]
	v_exp_f32_e32 v22, v22
	v_pk_mul_f32 v[18:19], v[30:31], v[18:19]
	v_mul_f32_e32 v30, 0xbfb8aa3b, v32
	v_exp_f32_e32 v30, v30
	v_mul_f32_e32 v31, 0xbfb8aa3b, v33
	v_exp_f32_e32 v31, v31
	v_pk_mul_f32 v[18:19], v[38:39], v[18:19]
	v_lshlrev_b32_e32 v38, 16, v55
	v_cvt_pk_bf16_f32 v18, v18, v19
	v_add_f32_e32 v19, 1.0, v30
	v_rcp_f32_e32 v30, v19
	v_add_f32_e32 v19, 1.0, v31
	v_rcp_f32_e32 v31, v19
	v_and_b32_e32 v39, 0xffff0000, v55
	v_pk_mul_f32 v[20:21], v[20:21], v[38:39]
	v_mul_f32_e32 v19, 0xbfb8aa3b, v26
	v_pk_mul_f32 v[30:31], v[32:33], v[30:31]
	v_exp_f32_e32 v23, v23
	v_pk_mul_f32 v[20:21], v[20:21], v[30:31]
	v_exp_f32_e32 v30, v19
	v_mul_f32_e32 v19, 0xbfb8aa3b, v27
	v_exp_f32_e32 v31, v19
	v_cvt_pk_bf16_f32 v19, v20, v21
	v_add_f32_e32 v20, 1.0, v30
	v_rcp_f32_e32 v20, v20
	v_add_f32_e32 v21, 1.0, v31
	v_rcp_f32_e32 v21, v21
	v_lshlrev_b32_e32 v30, 16, v56
	v_and_b32_e32 v31, 0xffff0000, v56
	v_pk_mul_f32 v[30:31], v[42:43], v[30:31]
	v_pk_mul_f32 v[20:21], v[26:27], v[20:21]
	v_mul_f32_e32 v26, 0xbfb8aa3b, v28
	v_exp_f32_e32 v26, v26
	v_mul_f32_e32 v27, 0xbfb8aa3b, v29
	v_exp_f32_e32 v27, v27
	v_pk_mul_f32 v[20:21], v[30:31], v[20:21]
	v_lshlrev_b32_e32 v30, 16, v57
	v_cvt_pk_bf16_f32 v20, v20, v21
	v_add_f32_e32 v21, 1.0, v26
	v_rcp_f32_e32 v26, v21
	v_add_f32_e32 v21, 1.0, v27
	v_rcp_f32_e32 v27, v21
	v_and_b32_e32 v31, 0xffff0000, v57
	v_pk_mul_f32 v[30:31], v[40:41], v[30:31]
	v_add_u32_e32 v38, 0xb0, v154
	v_pk_mul_f32 v[26:27], v[28:29], v[26:27]
	v_ashrrev_i32_e32 v39, 31, v38
	v_pk_mul_f32 v[26:27], v[30:31], v[26:27]
	v_lshlrev_b64 v[42:43], 11, v[38:39]
	v_cvt_pk_bf16_f32 v21, v26, v27
	global_store_dwordx4 v[60:61], v[18:21], off
	v_lshl_add_u64 v[44:45], v[152:153], 0, v[42:43]
	s_nop 0
	v_add_f32_e32 v18, 1.0, v22
	v_add_f32_e32 v19, 1.0, v23
	v_mul_f32_e32 v20, 0xbfb8aa3b, v24
	v_mul_f32_e32 v21, 0xbfb8aa3b, v25
	v_mul_f32_e32 v22, 0xbfb8aa3b, v36
	v_mul_f32_e32 v23, 0xbfb8aa3b, v37
	v_mul_f32_e32 v24, 0xbfb8aa3b, v34
	v_mul_f32_e32 v25, 0xbfb8aa3b, v35
	v_exp_f32_e32 v20, v20
	v_exp_f32_e32 v21, v21
	v_exp_f32_e32 v22, v22
	v_exp_f32_e32 v23, v23
	v_exp_f32_e32 v24, v24
	v_exp_f32_e32 v25, v25
	v_add_f32_e32 v20, 1.0, v20
	v_add_f32_e32 v21, 1.0, v21
	v_add_f32_e32 v22, 1.0, v22
	v_add_f32_e32 v23, 1.0, v23
	v_add_f32_e32 v24, 1.0, v24
	v_add_f32_e32 v25, 1.0, v25
	v_rcp_f32_e32 v18, v18
	v_rcp_f32_e32 v19, v19
	v_rcp_f32_e32 v20, v20
	v_rcp_f32_e32 v21, v21
	v_rcp_f32_e32 v22, v22
	v_rcp_f32_e32 v23, v23
	v_rcp_f32_e32 v24, v24
	v_rcp_f32_e32 v25, v25
	v_cvt_pk_bf16_f32 v18, v18, v19
	v_cvt_pk_bf16_f32 v19, v20, v21
	v_cvt_pk_bf16_f32 v20, v22, v23
	v_cvt_pk_bf16_f32 v21, v24, v25
	v_lshl_add_u64 v[22:23], v[150:151], 0, v[58:59]
	global_store_dwordx4 v[22:23], v[18:21], off
	v_lshlrev_b64 v[22:23], 8, v[38:39]
	v_lshl_add_u64 v[26:27], s[44:45], 0, v[22:23]
	v_lshlrev_b64 v[18:19], 6, v[38:39]
	v_lshl_add_u64 v[18:19], v[138:139], 0, v[18:19]
	global_load_dwordx4 v[18:21], v[18:19], off
	s_nop 0
	global_load_dwordx4 v[22:25], v[26:27], off
	s_nop 0
	global_load_dwordx4 v[26:29], v[26:27], off offset:16
	s_nop 0
	global_load_dwordx4 v[30:33], v[140:141], off
	global_load_dwordx4 v[34:37], v[140:141], off offset:16
	global_load_dwordx4 v[38:41], v[44:45], off
	s_waitcnt vmcnt(5)
	v_mov_b32_e32 v46, v19
	v_mov_b32_e32 v47, v20
	v_mov_b32_e32 v19, v21
	v_pk_add_f32 v[18:19], v[46:47], v[18:19]
	s_waitcnt vmcnt(4)
	v_mov_b32_e32 v46, v22
	v_add_f32_e32 v18, v18, v19
	ds_bpermute_b32 v19, v170, v18
	s_waitcnt vmcnt(3)
	v_mov_b32_e32 v47, v26
	v_mov_b32_e32 v26, v23
	v_pk_add_f32 v[22:23], v[46:47], v[26:27]
	v_mov_b32_e32 v26, v24
	s_waitcnt lgkmcnt(0)
	v_add_f32_e32 v19, v18, v19
	ds_bpermute_b32 v21, v155, v19
	v_mov_b32_e32 v27, v28
	v_mov_b32_e32 v28, v25
	v_pk_add_f32 v[24:25], v[26:27], v[28:29]
	s_waitcnt vmcnt(0)
	v_and_b32_e32 v29, 0xffff0000, v38
	v_pk_add_f32 v[22:23], v[22:23], v[24:25]
	s_nop 0
	v_mov_b32_e32 v18, v22
	v_mov_b32_e32 v20, v23
	s_waitcnt lgkmcnt(0)
	v_pk_add_f32 v[18:19], v[18:19], v[20:21]
	s_nop 0
	v_pk_fma_f32 v[18:19], v[18:19], s[18:19], v[156:157] op_sel_hi:[1,1,0]
	s_nop 0
	v_mul_f32_e32 v20, 0x4b800000, v19
	v_cmp_gt_f32_e32 vcc, s60, v19
	s_nop 1
	v_cndmask_b32_e32 v19, v19, v20, vcc
	v_rsq_f32_e32 v19, v19
	s_nop 0
	v_mul_f32_e32 v20, 0x45800000, v19
	v_cndmask_b32_e32 v20, v19, v20, vcc
	v_mul_f32_e32 v19, 0x4b800000, v18
	v_cmp_gt_f32_e32 vcc, s60, v18
	v_pk_mul_f32 v[16:17], v[16:17], v[20:21] op_sel_hi:[1,0]
	v_pk_mul_f32 v[14:15], v[14:15], v[20:21] op_sel_hi:[1,0]
	v_cndmask_b32_e32 v18, v18, v19, vcc
	v_rsq_f32_e32 v22, v18
	v_pk_mul_f32 v[12:13], v[12:13], v[20:21] op_sel_hi:[1,0]
	v_pk_mul_f32 v[10:11], v[10:11], v[20:21] op_sel_hi:[1,0]
	v_pk_mul_f32 v[8:9], v[8:9], v[20:21] op_sel_hi:[1,0]
	v_pk_mul_f32 v[6:7], v[6:7], v[20:21] op_sel_hi:[1,0]
	v_pk_mul_f32 v[18:19], v[4:5], v[20:21] op_sel_hi:[1,0]
	v_pk_mul_f32 v[20:21], v[2:3], v[20:21] op_sel_hi:[1,0]
	v_mul_f32_e32 v2, 0x45800000, v22
	v_cndmask_b32_e32 v2, v22, v2, vcc
	v_pk_mul_f32 v[4:5], v[32:33], v[2:3] op_sel_hi:[1,0]
	v_pk_mul_f32 v[22:23], v[30:31], v[2:3] op_sel_hi:[1,0]
	v_pk_mul_f32 v[24:25], v[36:37], v[2:3] op_sel_hi:[1,0]
	v_mul_f32_e32 v3, 0xbfb8aa3b, v14
	v_mul_f32_e32 v26, 0xbfb8aa3b, v15
	v_exp_f32_e32 v3, v3
	v_exp_f32_e32 v28, v26
	v_mul_f32_e32 v6, 0xbfb8aa3b, v6
	v_mul_f32_e32 v7, 0xbfb8aa3b, v7
	v_pk_mul_f32 v[26:27], v[34:35], v[2:3] op_sel_hi:[1,0]
	v_add_f32_e32 v2, 1.0, v3
	v_add_f32_e32 v3, 1.0, v28
	v_rcp_f32_e32 v2, v2
	v_rcp_f32_e32 v3, v3
	v_lshlrev_b32_e32 v28, 16, v38
	v_pk_mul_f32 v[22:23], v[22:23], v[28:29]
	v_exp_f32_e32 v6, v6
	v_pk_mul_f32 v[2:3], v[14:15], v[2:3]
	v_mul_f32_e32 v14, 0xbfb8aa3b, v16
	v_exp_f32_e32 v14, v14
	v_mul_f32_e32 v15, 0xbfb8aa3b, v17
	v_exp_f32_e32 v15, v15
	v_pk_mul_f32 v[2:3], v[22:23], v[2:3]
	v_lshlrev_b32_e32 v22, 16, v39
	v_cvt_pk_bf16_f32 v2, v2, v3
	v_add_f32_e32 v3, 1.0, v14
	v_rcp_f32_e32 v14, v3
	v_add_f32_e32 v3, 1.0, v15
	v_rcp_f32_e32 v15, v3
	v_and_b32_e32 v23, 0xffff0000, v39
	v_pk_mul_f32 v[4:5], v[4:5], v[22:23]
	v_mul_f32_e32 v3, 0xbfb8aa3b, v10
	v_pk_mul_f32 v[14:15], v[16:17], v[14:15]
	v_exp_f32_e32 v7, v7
	v_pk_mul_f32 v[4:5], v[4:5], v[14:15]
	v_exp_f32_e32 v14, v3
	v_mul_f32_e32 v3, 0xbfb8aa3b, v11
	v_exp_f32_e32 v15, v3
	v_cvt_pk_bf16_f32 v3, v4, v5
	v_add_f32_e32 v4, 1.0, v14
	v_rcp_f32_e32 v4, v4
	v_add_f32_e32 v5, 1.0, v15
	v_rcp_f32_e32 v5, v5
	v_lshlrev_b32_e32 v14, 16, v40
	v_and_b32_e32 v15, 0xffff0000, v40
	v_pk_mul_f32 v[14:15], v[26:27], v[14:15]
	v_pk_mul_f32 v[4:5], v[10:11], v[4:5]
	v_mul_f32_e32 v10, 0xbfb8aa3b, v12
	v_exp_f32_e32 v10, v10
	v_mul_f32_e32 v11, 0xbfb8aa3b, v13
	v_exp_f32_e32 v11, v11
	v_pk_mul_f32 v[4:5], v[14:15], v[4:5]
	v_lshlrev_b32_e32 v14, 16, v41
	v_cvt_pk_bf16_f32 v4, v4, v5
	v_add_f32_e32 v5, 1.0, v10
	v_rcp_f32_e32 v10, v5
	v_add_f32_e32 v5, 1.0, v11
	v_rcp_f32_e32 v11, v5
	v_and_b32_e32 v15, 0xffff0000, v41
	v_pk_mul_f32 v[14:15], v[24:25], v[14:15]
	s_andn2_b64 vcc, exec, s[0:1]
	v_pk_mul_f32 v[10:11], v[12:13], v[10:11]
	s_mov_b64 s[0:1], -1
	v_pk_mul_f32 v[10:11], v[14:15], v[10:11]
	s_nop 0
	v_cvt_pk_bf16_f32 v5, v10, v11
	global_store_dwordx4 v[44:45], v[2:5], off
	s_nop 1
	v_add_f32_e32 v2, 1.0, v6
	v_add_f32_e32 v3, 1.0, v7
	v_mul_f32_e32 v4, 0xbfb8aa3b, v8
	v_mul_f32_e32 v5, 0xbfb8aa3b, v9
	v_mul_f32_e32 v6, 0xbfb8aa3b, v20
	v_mul_f32_e32 v7, 0xbfb8aa3b, v21
	v_mul_f32_e32 v8, 0xbfb8aa3b, v18
	v_mul_f32_e32 v9, 0xbfb8aa3b, v19
	v_exp_f32_e32 v4, v4
	v_exp_f32_e32 v5, v5
	v_exp_f32_e32 v6, v6
	v_exp_f32_e32 v7, v7
	v_exp_f32_e32 v8, v8
	v_exp_f32_e32 v9, v9
	v_add_f32_e32 v4, 1.0, v4
	v_add_f32_e32 v5, 1.0, v5
	v_add_f32_e32 v6, 1.0, v6
	v_add_f32_e32 v7, 1.0, v7
	v_add_f32_e32 v8, 1.0, v8
	v_add_f32_e32 v9, 1.0, v9
	v_rcp_f32_e32 v2, v2
	v_rcp_f32_e32 v3, v3
	v_rcp_f32_e32 v4, v4
	v_rcp_f32_e32 v5, v5
	v_rcp_f32_e32 v6, v6
	v_rcp_f32_e32 v7, v7
	v_rcp_f32_e32 v8, v8
	v_rcp_f32_e32 v9, v9
	v_cvt_pk_bf16_f32 v2, v2, v3
	v_cvt_pk_bf16_f32 v3, v4, v5
	v_cvt_pk_bf16_f32 v4, v6, v7
	v_cvt_pk_bf16_f32 v5, v8, v9
	v_lshl_add_u64 v[6:7], v[150:151], 0, v[42:43]
	global_store_dwordx4 v[6:7], v[2:5], off
	s_cbranch_vccnz .LBB0_2908
	s_andn2_b64 vcc, exec, s[8:9]
	s_cbranch_vccnz .LBB0_2907
	s_barrier
	s_branch .LBB0_2907
